# context out units on XCD 7 (jloc<24), layer-0 gemm-out tile ranges 71/70/32 per XCD so XCD 7 runs one tile per WG incl. the 16 context tiles
# speedup vs baseline: 1.0211x; 1.0038x over previous
.LBB0_1212:
	s_or_b64 exec, exec, s[0:1]
	s_waitcnt lgkmcnt(0)
	s_barrier
	v_readlane_b32 s0, v255, 25
	v_readlane_b32 s1, v255, 0
	s_cmp_lg_u32 s0, 0
	s_cbranch_scc1 .Lcx_mark7
	s_cmpk_lg_i32 s36, 0x100
	s_cbranch_scc1 .Lcx_mark7
	s_cmp_ge_u32 s1, 248
	s_cbranch_scc1 .Lcx_attn
	s_and_b32 s2, s1, 7
	s_cmp_lg_u32 s2, 7
	s_cbranch_scc1 .Lcx_mark7
	s_lshr_b32 s1, s1, 3
	s_cmp_lt_u32 s1, 24
	s_cbranch_scc0 .Lcx_mark7
	s_lshr_b32 s2, s1, 3
	s_mulk_i32 s2, 0x108
	s_bfe_u32 s3, s1, 0x10002
	s_mulk_i32 s3, 0x84
	s_and_b32 s1, s1, 3
	s_add_i32 s2, s2, s3
	s_add_i32 s29, s2, s1
	s_movk_i32 s8, 0x108
	s_mov_b32 s52, 0x10800
	s_mov_b32 s53, 0x8100
	s_mov_b32 s59, 0x3195000
	v_cvt_f32_u32_e32 v0, s8
	v_readlane_b32 s0, v255, 25
	s_sub_i32 s4, 0, s8
	v_readlane_b32 s1, v255, 26
	v_rcp_iflag_f32_e32 v0, v0
	s_mov_b32 s2, s0
	s_lshl_b32 s48, s0, 8
	s_lshl_b32 s10, s0, 10
	v_mul_f32_e32 v0, 0x4f7ffffe, v0
	v_cvt_u32_f32_e32 v0, v0
	s_lshl_b32 s24, s0, 1
	s_lshl_b32 s0, s0, 9
	s_mov_b32 s1, s49
	v_readfirstlane_b32 s5, v0
	s_mul_i32 s4, s4, s5
	s_lshl_b32 s14, s2, 11
	s_lshl_b32 s25, s2, 3
	s_lshl_b32 s26, s2, 2
	s_lshl_b32 s27, s2, 12
	s_lshl_b32 s2, s2, 6
	s_mov_b32 s3, s49
	s_mul_hi_u32 s4, s5, s4
	s_mov_b32 s11, s49
	s_mov_b32 s15, s49
	s_add_i32 s28, s5, s4
	s_lshl_b64 s[16:17], s[2:3], 2
	s_lshl_b64 s[18:19], s[0:1], 2
	s_mov_b32 s9, 0
	s_mov_b64 s[100:101], 0
	s_branch .LBB0_694

.Lcx_mark7:
	ds_read_b64 v[0:1], v129 offset:232
	v_readlane_b32 s0, v255, 25
	v_readlane_b32 s1, v255, 26
	s_mov_b32 s1, s49
	s_lshl_b64 s[0:1], s[0:1], 21
	s_waitcnt lgkmcnt(0)
	v_lshl_add_u64 v[2:3], v[0:1], 0, s[0:1]
	v_readlane_b32 s0, v255, 23
	v_readlane_b32 s1, v255, 24
	s_and_b64 s[0:1], exec, s[0:1]
	s_cselect_b32 s10, 0x42, 64
	v_readlane_b32 s0, v255, 5
	v_mov_b32_e32 v4, v206
	s_mul_i32 s15, s10, s0
	s_lshl_b32 s11, s10, 3
	s_add_i32 s0, s15, s10
	v_lshlrev_b32_e32 v8, 4, v4
	s_min_u32 s14, s11, s0
	v_and_b32_e32 v128, 0x70, v8
	v_readlane_b32 s0, v255, 6
	s_add_i32 s15, s15, s0
	s_cmp_lg_u32 s10, 0x42
	s_cbranch_scc1 .Lcx_map_done
	s_cmpk_lg_i32 s36, 0x100
	s_cbranch_scc1 .Lcx_map_done
	v_readlane_b32 s1, v255, 5
	s_mul_i32 s15, s1, 0x47
	s_add_i32 s14, s15, 0x47
	s_min_u32 s14, s14, 0x1f0
	s_cmp_eq_u32 s1, 7
	s_cselect_b32 s15, 0x1f0, s15
	s_cselect_b32 s14, 0x210, s14
	s_add_i32 s15, s15, s0
.Lcx_map_done:
	v_lshl_add_u64 v[0:1], v[0:1], 0, v[128:129]
	s_mov_b64 s[0:1], 0x1095000
	v_lshl_add_u64 v[178:179], v[0:1], 0, s[0:1]
	v_lshl_add_u64 v[0:1], v[2:3], 0, v[128:129]
	s_mov_b64 s[0:1], 0xc80000
	v_lshl_add_u64 v[180:181], v[0:1], 0, s[0:1]
	v_ashrrev_i32_e32 v1, 1, v4
	v_and_b32_e32 v6, 31, v4
	v_and_b32_e32 v202, 0xffffffc0, v1
	v_bfe_u32 v7, v4, 5, 1
	s_movk_i32 s0, 0x90
	v_or_b32_e32 v1, v202, v6
	v_mul_lo_u32 v1, v1, s0
	v_lshlrev_b32_e32 v2, 4, v7
	v_ashrrev_i32_e32 v200, 3, v4
	v_add3_u32 v203, s57, v1, v2
	v_and_b32_e32 v1, 0x5f, v4
	v_mul_lo_u32 v0, v200, s0
	v_mul_u32_u24_e32 v1, 0x90, v1
	v_readlane_b32 s0, v255, 15
	v_ashrrev_i32_e32 v5, 6, v4
	v_add3_u32 v201, s57, v128, v0
	v_add3_u32 v234, s0, v128, v0
	v_add3_u32 v235, s0, v1, v2
	s_movk_i32 s0, 0x4400
	v_add3_u32 v204, s57, v1, v2
	v_mul_lo_u32 v0, v5, s0
	v_lshlrev_b32_e32 v2, 2, v4
	v_add_u32_e32 v0, 0x100, v0
	v_lshlrev_b32_e32 v1, 2, v6
	v_and_b32_e32 v2, 60, v2
	v_bfe_u32 v237, v4, 4, 2
	v_mul_u32_u24_e32 v3, 0x440, v7
	v_and_or_b32 v236, v4, 64, v2
	v_lshl_add_u32 v2, v2, 2, v0
	v_add3_u32 v238, v0, v1, v3
	v_mul_u32_u24_e32 v0, 0x110, v237
	v_mov_b32_e32 v210, 0xc0c0
	v_mov_b32_e32 v209, 0xacac
	v_mov_b32_e32 v208, v252
	v_cmp_lt_i32_e64 s[2:3], 3, v5
	v_add_u32_e32 v205, 0xd800, v201
	v_or_b32_e32 v239, 4, v237
	v_or_b32_e32 v240, 8, v237
	v_or_b32_e32 v241, 12, v237
	v_or_b32_e32 v242, 16, v237
	v_or_b32_e32 v243, 20, v237
	v_or_b32_e32 v244, 24, v237
	v_or_b32_e32 v245, 28, v237
	v_or_b32_e32 v246, 32, v237
	v_or_b32_e32 v247, 36, v237
	v_or_b32_e32 v248, 40, v237
	v_or_b32_e32 v249, 44, v237
	v_or_b32_e32 v250, 48, v237
	v_or_b32_e32 v251, 52, v237
	v_or_b32_e32 v252, 56, v237
	v_or_b32_e32 v253, 60, v237
	s_mov_b32 s16, 0
	v_add_u32_e32 v254, v2, v0
	s_branch .LBB0_1216
